# attention units: global atomic queue + LDS broadcast + second barrier replaced by a static serpentine schedule (unit = k*G + bx or k*G + G-1-bx)
# speedup vs baseline: 1.0050x; 1.0035x over previous
.LBB0_786:
	s_andn2_b64 vcc, exec, s[4:5]
	s_cbranch_vccnz .LBB0_856
	v_readlane_b32 s4, v254, 0
	v_readlane_b32 s5, v254, 1
	s_load_dwordx4 s[36:39], s[4:5], 0xb8
	v_readlane_b32 s4, v253, 32
	v_readlane_b32 s5, v253, 33
	s_mov_b32 s7, s5
	v_readlane_b32 s4, v253, 36
	s_waitcnt lgkmcnt(0)
	s_add_u32 s62, s36, 0x3cb2000
	s_addc_u32 s63, s37, 0
	s_add_u32 s70, s38, 0x11139000
	s_addc_u32 s71, s39, 0
	s_add_u32 s88, s38, 0x131b9000
	s_addc_u32 s89, s39, 0
	s_add_u32 s54, s38, 0x8f21000
	s_addc_u32 s55, s39, 0
	v_readlane_b32 s5, v253, 37
	s_add_u32 s44, s38, 0xf0b1000
	s_mov_b32 s5, s7
	s_addc_u32 s45, s39, 0
	s_lshl_b32 s6, s4, 4
	v_writelane_b32 v253, s4, 32
	v_mov_b32_e32 v127, v192
	v_mov_b32_e32 v125, v173
	v_writelane_b32 v253, s5, 33
	s_lshl_b64 s[4:5], s[6:7], 2
	s_add_u32 s4, s38, s4
	v_ashrrev_i32_e32 v122, 3, v127
	s_addc_u32 s5, s39, s5
	v_max_i32_e32 v0, 48, v122
	v_writelane_b32 v253, s4, 38
	v_readfirstlane_b32 s0, v127
	v_subrev_u32_e32 v124, 48, v0
	v_lshlrev_b32_e32 v0, 3, v127
	v_and_b32_e32 v154, 63, v127
	v_writelane_b32 v253, s5, 39
	v_bfe_u32 v1, v127, 4, 2
	s_ashr_i32 s0, s0, 1
	v_and_b32_e32 v172, 48, v127
	v_and_b32_e32 v126, 56, v0
	s_movk_i32 s4, 0x48
	v_and_b32_e32 v155, 15, v127
	s_and_b32 s85, s0, 0xffffffe0
	v_lshlrev_b32_e32 v157, 3, v1
	v_lshl_add_u64 v[120:121], s[54:55], 0, v[172:173]
	v_max_u32_e32 v0, 48, v126
	v_max_u32_e32 v2, 48, v154
	v_mul_lo_u32 v3, v122, s4
	v_lshlrev_b32_e32 v158, 2, v1
	v_lshlrev_b32_e32 v1, 2, v154
	v_lshlrev_b32_e32 v172, 1, v126
	v_cmp_eq_u32_e32 vcc, 0, v127
	v_or_b32_e32 v156, s85, v155
	v_ashrrev_i32_e32 v123, 31, v122
	v_cmp_gt_i32_e64 s[4:5], 64, v127
	s_or_b32 s93, s0, 31
	v_mul_u32_u24_e32 v159, 0x48, v155
	v_xor_b32_e32 v160, 64, v1
	v_xor_b32_e32 v161, 0x80, v1
	v_lshl_add_u64 v[128:129], s[70:71], 0, v[172:173]
	v_sub_u32_e32 v162, 0, v157
	s_mov_b64 s[66:67], 0
	v_lshlrev_b32_e32 v130, 1, v0
	v_lshlrev_b32_e32 v132, 2, v2
	v_lshlrev_b32_e32 v163, 1, v3
	v_mov_b32_e32 v235, 0
	s_branch .LBB0_790

.LBB0_790:
	s_waitcnt vmcnt(0)
	s_barrier
	v_readfirstlane_b32 s100, v235
	s_nop 3
	s_mul_i32 s101, s100, s42
	s_sub_i32 s0, s42, 1
	s_sub_i32 s0, s0, s2
	s_bitcmp0_b32 s100, 0
	s_cselect_b32 s0, s2, s0
	s_add_i32 s101, s101, s0
	v_add_u32_e32 v235, 1, v235
	v_mov_b32_e32 v0, s101
	s_movk_i32 s0, 0x480
	s_mov_b64 s[8:9], -1
	v_cmp_gt_i32_e64 s[6:7], s0, v0
	s_and_saveexec_b64 s[68:69], s[6:7]
	s_cbranch_execz .LBB0_789
	v_ashrrev_i32_e32 v1, 31, v0
	v_lshrrev_b32_e32 v1, 25, v1
	v_add_u32_e32 v1, v0, v1
	v_ashrrev_i32_e32 v8, 7, v1
	v_and_b32_e32 v1, 0xffffff80, v1
	v_sub_u32_e32 v0, v0, v1
	v_mov_b32_e32 v1, 11
	v_lshrrev_b16_sdwa v1, v1, sext(v0) dst_sel:DWORD dst_unused:UNUSED_PAD src0_sel:DWORD src1_sel:BYTE_0
	v_and_b32_e32 v1, 15, v1
	v_add_u16_e32 v1, v0, v1
	v_sub_u32_e32 v9, 8, v8
	v_ashrrev_i16_sdwa v2, v198, sext(v1) dst_sel:DWORD dst_unused:UNUSED_PAD src0_sel:DWORD src1_sel:BYTE_0
	s_movk_i32 s0, 0x810
	v_and_b32_e32 v1, 0xf0, v1
	v_mul_hi_i32_i24_sdwa v135, sext(v2), s0 dst_sel:DWORD dst_unused:UNUSED_PAD src0_sel:WORD_0 src1_sel:DWORD
	v_mul_i32_i24_sdwa v134, sext(v2), s0 dst_sel:DWORD dst_unused:UNUSED_PAD src0_sel:WORD_0 src1_sel:DWORD
	v_mul_hi_i32_i24_e32 v3, 0x2040, v0
	v_mul_i32_i24_e32 v2, 0x2040, v0
	v_lshlrev_b32_e32 v10, 8, v9
	v_sub_u16_e32 v4, v0, v1
	v_lshl_add_u64 v[140:141], s[62:63], 0, v[2:3]
	v_add_u32_e32 v164, v10, v156
	v_mov_b32_e32 v2, 6
	v_lshlrev_b32_sdwa v138, v2, sext(v4) dst_sel:DWORD dst_unused:UNUSED_PAD src0_sel:DWORD src1_sel:BYTE_0
	v_max_i32_e32 v6, 0xf0, v164
	v_ashrrev_i32_e32 v139, 31, v138
	v_add_u32_e32 v172, 0xffffff10, v6
	v_lshlrev_b64 v[2:3], 1, v[138:139]
	v_lshl_add_u64 v[6:7], v[134:135], 0, v[172:173]
	v_lshl_add_u64 v[4:5], v[120:121], 0, v[2:3]
	v_lshlrev_b64 v[6:7], 12, v[6:7]
	v_lshl_add_u64 v[6:7], v[4:5], 0, v[6:7]
	v_or_b32_e32 v139, 16, v164
	global_load_dwordx4 v[20:23], v[6:7], off
	global_load_dwordx4 v[24:27], v[6:7], off offset:64
	v_max_i32_e32 v6, 0xf0, v139
	v_add_u32_e32 v172, 0xffffff10, v6
	v_lshl_add_u64 v[6:7], v[134:135], 0, v[172:173]
	v_lshlrev_b64 v[6:7], 12, v[6:7]
	v_ashrrev_i32_e32 v1, 31, v0
	v_lshl_add_u64 v[4:5], v[4:5], 0, v[6:7]
	global_load_dwordx4 v[28:31], v[4:5], off
	global_load_dwordx4 v[32:35], v[4:5], off offset:64
	v_lshl_add_u64 v[4:5], v[134:135], 0, v[124:125]
	v_lshlrev_b64 v[0:1], 6, v[0:1]
	v_lshlrev_b64 v[4:5], 11, v[4:5]
	v_lshl_add_u64 v[0:1], v[0:1], 0, v[122:123]
	v_mov_b64_e32 v[6:7], s[88:89]
	v_lshl_add_u64 v[4:5], s[70:71], 0, v[4:5]
	v_mad_u64_u32 v[144:145], s[6:7], v0, s52, v[6:7]
	v_lshl_add_u64 v[4:5], v[4:5], 0, v[2:3]
	v_lshlrev_b32_e32 v142, 1, v126
	v_mov_b32_e32 v143, v173
	v_mad_i32_i24 v145, v1, s52, v145
	v_mov_b32_e32 v131, v173
	v_lshlrev_b32_e32 v165, 2, v9
	v_lshl_add_u64 v[4:5], v[4:5], 0, v[142:143]
	v_lshl_add_u64 v[0:1], v[144:145], 0, v[130:131]
	v_mov_b32_e32 v133, v173
	v_or_b32_e32 v166, 3, v165
	global_load_dwordx4 v[36:39], v[4:5], off
	global_load_dwordx4 v[40:43], v[0:1], off offset:-96
	v_lshl_add_u64 v[0:1], v[140:141], 0, v[132:133]
	global_load_dword v131, v[0:1], off offset:-192
	v_min_u32_e32 v0, 4, v166
	v_lshl_add_u32 v6, v0, 6, v201
	v_add_u32_e32 v0, v6, v122
	v_max_i32_e32 v172, 0, v0
	v_lshl_add_u64 v[0:1], v[134:135], 0, v[172:173]
	v_lshlrev_b64 v[0:1], 11, v[0:1]
	v_lshl_add_u64 v[0:1], s[70:71], 0, v[0:1]
	v_add_u32_e32 v4, v6, v126
	v_lshl_add_u64 v[0:1], v[0:1], 0, v[2:3]
	v_max_i32_e32 v4, 0, v4
	v_lshl_add_u64 v[0:1], v[0:1], 0, v[142:143]
	v_lshlrev_b32_e32 v172, 1, v4
	v_lshl_add_u64 v[4:5], v[144:145], 0, v[172:173]
	global_load_dwordx4 v[44:47], v[0:1], off
	global_load_dwordx4 v[48:51], v[4:5], off
	v_add_u32_e32 v0, v6, v154
	v_max_i32_e32 v0, 0, v0
	v_lshlrev_b32_e32 v172, 2, v0
	v_lshl_add_u64 v[0:1], v[140:141], 0, v[172:173]
	global_load_dword v167, v[0:1], off
	v_min_u32_e32 v0, 5, v166
	v_lshl_add_u32 v6, v0, 6, v201
	v_add_u32_e32 v0, v6, v122
	v_max_i32_e32 v172, 0, v0
	v_lshl_add_u64 v[0:1], v[134:135], 0, v[172:173]
	v_lshlrev_b64 v[0:1], 11, v[0:1]
	v_lshl_add_u64 v[0:1], s[70:71], 0, v[0:1]
	v_add_u32_e32 v4, v6, v126
	v_lshl_add_u64 v[0:1], v[0:1], 0, v[2:3]
	v_max_i32_e32 v4, 0, v4
	v_lshl_add_u64 v[0:1], v[0:1], 0, v[142:143]
	v_lshlrev_b32_e32 v172, 1, v4
	v_lshl_add_u64 v[4:5], v[144:145], 0, v[172:173]
	global_load_dwordx4 v[52:55], v[0:1], off
	global_load_dwordx4 v[56:59], v[4:5], off
	v_add_u32_e32 v0, v6, v154
	v_max_i32_e32 v0, 0, v0
	v_lshlrev_b32_e32 v172, 2, v0
	v_lshl_add_u64 v[0:1], v[140:141], 0, v[172:173]
	global_load_dword v169, v[0:1], off
	v_sub_u32_e32 v0, 0, v8
	v_or_b32_e32 v1, v10, v155
	v_lshl_add_u64 v[146:147], v[128:129], 0, v[2:3]
	v_lshlrev_b32_e32 v0, 8, v0
	v_mov_b32_e32 v2, v173
	v_mov_b32_e32 v3, v173
	v_add_u32_e32 v133, s85, v1
	v_sub_u32_e32 v168, 0, v0
	v_mov_b32_e32 v172, v173
	v_mov_b32_e32 v0, v173
	v_mov_b32_e32 v1, v173
	v_mov_b64_e32 v[6:7], v[2:3]
	v_mov_b64_e32 v[10:11], v[2:3]
	v_mov_b64_e32 v[14:15], v[2:3]
	v_mov_b64_e32 v[18:19], v[2:3]
	v_mov_b64_e32 v[62:63], v[2:3]
	v_mov_b64_e32 v[66:67], v[2:3]
	v_mov_b64_e32 v[70:71], v[2:3]
	s_mov_b32 s60, s87
	s_mov_b32 s84, 0
	v_or_b32_e32 v143, 16, v133
	v_mov_b32_e32 v148, 0xff800000
	s_mov_b64 s[34:35], 0
	v_mov_b32_e32 v170, 0
	s_mov_b32 s87, 0
	v_mov_b64_e32 v[4:5], v[0:1]
	v_mov_b64_e32 v[8:9], v[0:1]
	v_mov_b64_e32 v[12:13], v[0:1]
	v_mov_b64_e32 v[16:17], v[0:1]
	v_mov_b64_e32 v[60:61], v[0:1]
	v_mov_b64_e32 v[64:65], v[0:1]
	v_mov_b64_e32 v[68:69], v[0:1]
	v_mov_b64_e32 v[136:137], v[172:173]
	v_mov_b32_e32 v149, 0xff800000
	s_branch .LBB0_798
